# variant: per-tile LDS-DMA issues spread inside the QK phase only (pairs 2/5/8 and QK end), none during PV
# baseline (speedup 1.0000x reference)
.LBB0_1425:
	s_add_i32 s13, s74, 0x8000
	s_mov_b32 s14, m0
	s_mov_b32 m0, s13
	s_nop 0
	global_load_lds_dwordx4 v[168:169], off
	s_mov_b32 m0, s14
	ds_read_b128 v[178:181], v211
	ds_read_b128 v[214:217], v211 offset:12288
	ds_read_b128 v[238:241], v210
	ds_read_b128 v[242:245], v210 offset:12288
	ds_read_b128 v[246:249], v209
	ds_read_b128 v[250:253], v209 offset:12288
	ds_read_b128 v[218:221], v193
	ds_read_b128 v[222:225], v193 offset:1024
	ds_read_b128 v[226:229], v193 offset:2048
	ds_read_b128 v[230:233], v193 offset:3072
	s_waitcnt lgkmcnt(9)
	v_mfma_f32_32x32x16_bf16 v[114:129], v[178:181], v[158:161], v[82:97]
	s_waitcnt lgkmcnt(8)
	v_mfma_f32_32x32x16_bf16 v[98:113], v[214:217], v[158:161], v[82:97]
	ds_read_b128 v[178:181], v208
	ds_read_b128 v[214:217], v208 offset:12288
	s_waitcnt lgkmcnt(9)
	v_mfma_f32_32x32x16_bf16 v[114:129], v[238:241], v[154:157], v[114:129]
	s_waitcnt lgkmcnt(8)
	v_mfma_f32_32x32x16_bf16 v[98:113], v[242:245], v[154:157], v[98:113]
	ds_read_b128 v[238:241], v207
	ds_read_b128 v[242:245], v207 offset:12288
	s_waitcnt lgkmcnt(9)
	v_mfma_f32_32x32x16_bf16 v[114:129], v[246:249], v[150:153], v[114:129]
	s_waitcnt lgkmcnt(8)
	v_mfma_f32_32x32x16_bf16 v[98:113], v[250:253], v[150:153], v[98:113]
	ds_read_b128 v[246:249], v206
	ds_read_b128 v[250:253], v206 offset:12288
	s_add_i32 s13, s75, 0x8000
	s_mov_b32 s14, m0
	s_mov_b32 m0, s13
	s_nop 0
	global_load_lds_dwordx4 v[170:171], off
	s_mov_b32 m0, s14
	s_waitcnt lgkmcnt(5)
	v_mfma_f32_32x32x16_bf16 v[114:129], v[178:181], v[146:149], v[114:129]
	s_waitcnt lgkmcnt(4)
	v_mfma_f32_32x32x16_bf16 v[98:113], v[214:217], v[146:149], v[98:113]
	ds_read_b128 v[178:181], v205
	ds_read_b128 v[214:217], v205 offset:12288
	s_waitcnt lgkmcnt(5)
	v_mfma_f32_32x32x16_bf16 v[114:129], v[238:241], v[142:145], v[114:129]
	s_waitcnt lgkmcnt(4)
	v_mfma_f32_32x32x16_bf16 v[98:113], v[242:245], v[142:145], v[98:113]
	ds_read_b128 v[238:241], v204
	ds_read_b128 v[242:245], v204 offset:12288
	s_waitcnt lgkmcnt(5)
	v_mfma_f32_32x32x16_bf16 v[114:129], v[246:249], v[138:141], v[114:129]
	s_waitcnt lgkmcnt(4)
	v_mfma_f32_32x32x16_bf16 v[98:113], v[250:253], v[138:141], v[98:113]
	ds_read_b128 v[246:249], v203
	ds_read_b128 v[250:253], v203 offset:12288
	s_add_i32 s13, s5, 0x8000
	s_mov_b32 s14, m0
	s_mov_b32 m0, s13
	s_nop 0
	global_load_lds_dwordx4 v[172:173], off
	s_mov_b32 m0, s14
	s_waitcnt lgkmcnt(5)
	v_mfma_f32_32x32x16_bf16 v[114:129], v[178:181], v[134:137], v[114:129]
	s_waitcnt lgkmcnt(4)
	v_mfma_f32_32x32x16_bf16 v[98:113], v[214:217], v[134:137], v[98:113]
	ds_read_b128 v[178:181], v202
	ds_read_b128 v[214:217], v202 offset:12288
	s_waitcnt lgkmcnt(5)
	v_mfma_f32_32x32x16_bf16 v[114:129], v[238:241], v[130:133], v[114:129]
	s_waitcnt lgkmcnt(4)
	v_mfma_f32_32x32x16_bf16 v[98:113], v[242:245], v[130:133], v[98:113]
	ds_read_b128 v[238:241], v201
	ds_read_b128 v[242:245], v201 offset:12288
	s_waitcnt lgkmcnt(5)
	v_mfma_f32_32x32x16_bf16 v[114:129], v[246:249], v[218:221], v[114:129]
	s_waitcnt lgkmcnt(4)
	v_mfma_f32_32x32x16_bf16 v[98:113], v[250:253], v[218:221], v[98:113]
	ds_read_b128 v[246:249], v200
	ds_read_b128 v[250:253], v200 offset:12288
	s_add_i32 s13, s86, 0x0
	s_mov_b32 s14, m0
	s_mov_b32 m0, s13
	s_nop 0
	global_load_lds_dwordx4 v[174:175], off
	s_mov_b32 m0, s14
	s_waitcnt lgkmcnt(5)
	v_mfma_f32_32x32x16_bf16 v[114:129], v[178:181], v[222:225], v[114:129]
	s_waitcnt lgkmcnt(4)
	v_mfma_f32_32x32x16_bf16 v[98:113], v[214:217], v[222:225], v[98:113]
	s_waitcnt lgkmcnt(3)
	v_mfma_f32_32x32x16_bf16 v[114:129], v[238:241], v[226:229], v[114:129]
	s_waitcnt lgkmcnt(2)
	v_mfma_f32_32x32x16_bf16 v[98:113], v[242:245], v[226:229], v[98:113]
	s_waitcnt lgkmcnt(1)
	v_mfma_f32_32x32x16_bf16 v[114:129], v[246:249], v[230:233], v[114:129]
	s_waitcnt lgkmcnt(0)
	v_mfma_f32_32x32x16_bf16 v[98:113], v[250:253], v[230:233], v[98:113]
	s_add_i32 s13, s3, 0x0
	s_mov_b32 s14, m0
	s_mov_b32 m0, s13
	s_nop 0
	global_load_lds_dwordx4 v[176:177], off
	s_mov_b32 m0, s14
	s_sub_i32 s0, s12, 64
	s_cmp_le_i32 s0, s96
	s_cbranch_scc1 .LBB0_1427
	v_add_u32_e32 v165, 0x5b, v212
	v_cmp_lt_i32_e32 vcc, -1, v165
	s_nop 4
	v_cndmask_b32_e32 v114, v185, v114, vcc
	v_cmp_lt_i32_e32 vcc, 31, v165
	v_add_u32_e32 v165, 0x5a, v212
	s_nop 0
	v_cndmask_b32_e32 v98, v185, v98, vcc
	v_cmp_lt_i32_e32 vcc, -1, v165
	s_nop 1
	v_cndmask_b32_e32 v115, v185, v115, vcc
	v_cmp_lt_i32_e32 vcc, 31, v165
	v_add_u32_e32 v165, 0x59, v212
	s_nop 0
	v_cndmask_b32_e32 v99, v185, v99, vcc
	v_cmp_lt_i32_e32 vcc, -1, v165
	s_nop 1
	v_cndmask_b32_e32 v116, v185, v116, vcc
	v_cmp_lt_i32_e32 vcc, 31, v165
	v_add_u32_e32 v165, 0x58, v212
	s_nop 0
	v_cndmask_b32_e32 v100, v185, v100, vcc
	v_cmp_lt_i32_e32 vcc, -1, v165
	s_nop 1
	v_cndmask_b32_e32 v117, v185, v117, vcc
	v_cmp_lt_i32_e32 vcc, 31, v165
	v_add_u32_e32 v165, 0x53, v212
	s_nop 0
	v_cndmask_b32_e32 v101, v185, v101, vcc
	v_cmp_lt_i32_e32 vcc, -1, v165
	s_nop 1
	v_cndmask_b32_e32 v118, v185, v118, vcc
	v_cmp_lt_i32_e32 vcc, 31, v165
	v_add_u32_e32 v165, 0x52, v212
	s_nop 0
	v_cndmask_b32_e32 v102, v185, v102, vcc
	v_cmp_lt_i32_e32 vcc, -1, v165
	s_nop 1
	v_cndmask_b32_e32 v119, v185, v119, vcc
	v_cmp_lt_i32_e32 vcc, 31, v165
	v_add_u32_e32 v165, 0x51, v212
	s_nop 0
	v_cndmask_b32_e32 v103, v185, v103, vcc
	v_cmp_lt_i32_e32 vcc, -1, v165
	s_nop 1
	v_cndmask_b32_e32 v120, v185, v120, vcc
	v_cmp_lt_i32_e32 vcc, 31, v165
	v_add_u32_e32 v165, 0x50, v212
	s_nop 0
	v_cndmask_b32_e32 v104, v185, v104, vcc
	v_cmp_lt_i32_e32 vcc, -1, v165
	s_nop 1
	v_cndmask_b32_e32 v121, v185, v121, vcc
	v_cmp_lt_i32_e32 vcc, 31, v165
	v_add_u32_e32 v165, 0x4b, v212
	s_nop 0
	v_cndmask_b32_e32 v105, v185, v105, vcc
	v_cmp_lt_i32_e32 vcc, -1, v165
	s_nop 1
	v_cndmask_b32_e32 v122, v185, v122, vcc
	v_cmp_lt_i32_e32 vcc, 31, v165
	v_add_u32_e32 v165, 0x4a, v212
	s_nop 0
	v_cndmask_b32_e32 v106, v185, v106, vcc
	v_cmp_lt_i32_e32 vcc, -1, v165
	s_nop 1
	v_cndmask_b32_e32 v123, v185, v123, vcc
	v_cmp_lt_i32_e32 vcc, 31, v165
	v_add_u32_e32 v165, 0x49, v212
	s_nop 0
	v_cndmask_b32_e32 v107, v185, v107, vcc
	v_cmp_lt_i32_e32 vcc, -1, v165
	s_nop 1
	v_cndmask_b32_e32 v124, v185, v124, vcc
	v_cmp_lt_i32_e32 vcc, 31, v165
	v_add_u32_e32 v165, 0x48, v212
	s_nop 0
	v_cndmask_b32_e32 v108, v185, v108, vcc
	v_cmp_lt_i32_e32 vcc, -1, v165
	s_nop 1
	v_cndmask_b32_e32 v125, v185, v125, vcc
	v_cmp_lt_i32_e32 vcc, 31, v165
	v_add_u32_e32 v165, 0x43, v212
	s_nop 0
	v_cndmask_b32_e32 v109, v185, v109, vcc
	v_cmp_lt_i32_e32 vcc, -1, v165
	s_nop 1
	v_cndmask_b32_e32 v126, v185, v126, vcc
	v_cmp_lt_i32_e32 vcc, 31, v165
	v_add_u32_e32 v165, 0x42, v212
	s_nop 0
	v_cndmask_b32_e32 v110, v185, v110, vcc
	v_cmp_lt_i32_e32 vcc, -1, v165
	s_nop 1
	v_cndmask_b32_e32 v127, v185, v127, vcc
	v_cmp_lt_i32_e32 vcc, 31, v165
	v_add_u32_e32 v165, 0x41, v212
	s_nop 0
	v_cndmask_b32_e32 v111, v185, v111, vcc
	v_cmp_lt_i32_e32 vcc, -1, v165
	s_nop 1
	v_cndmask_b32_e32 v128, v185, v128, vcc
	v_cmp_lt_i32_e32 vcc, 31, v165
	v_add_u32_e32 v165, 64, v212
	s_nop 0
	v_cndmask_b32_e32 v112, v185, v112, vcc
	v_cmp_lt_i32_e32 vcc, -1, v165
	s_nop 1
	v_cndmask_b32_e32 v129, v185, v129, vcc
	v_cmp_lt_i32_e32 vcc, 31, v165
	s_nop 1
	v_cndmask_b32_e32 v113, v185, v113, vcc

.LBB0_1431:
	v_exp_f32_e32 v114, v114
	v_exp_f32_e32 v215, v98
	v_exp_f32_e32 v98, v115
	v_exp_f32_e32 v115, v99
	v_exp_f32_e32 v99, v116
	v_exp_f32_e32 v116, v100
	v_exp_f32_e32 v100, v117
	v_exp_f32_e32 v117, v101
	v_exp_f32_e32 v101, v118
	v_exp_f32_e32 v118, v102
	v_exp_f32_e32 v102, v119
	v_exp_f32_e32 v119, v103
	v_exp_f32_e32 v103, v120
	v_exp_f32_e32 v120, v104
	v_exp_f32_e32 v104, v121
	v_exp_f32_e32 v121, v105
	v_exp_f32_e32 v105, v122
	v_exp_f32_e32 v122, v106
	v_exp_f32_e32 v106, v123
	v_exp_f32_e32 v123, v107
	v_exp_f32_e32 v107, v124
	v_exp_f32_e32 v124, v108
	v_exp_f32_e32 v108, v125
	v_exp_f32_e32 v125, v109
	v_exp_f32_e32 v109, v126
	v_exp_f32_e32 v126, v110
	v_exp_f32_e32 v110, v127
	v_exp_f32_e32 v127, v111
	v_exp_f32_e32 v111, v128
	v_exp_f32_e32 v128, v112
	v_exp_f32_e32 v112, v129
	v_add_f32_e32 v129, v114, v215
	v_add_f32_e32 v213, v98, v115
	v_add_f32_e32 v214, v99, v116
	v_add_f32_e32 v216, v100, v117
	v_exp_f32_e32 v113, v113
	v_add_f32_e32 v129, v129, v101
	v_add_f32_e32 v213, v213, v102
	v_add_f32_e32 v214, v214, v103
	v_add_f32_e32 v216, v216, v104
	v_mov_b32_e32 v165, v163
	v_add_f32_e32 v129, v129, v118
	v_add_f32_e32 v213, v213, v119
	v_add_f32_e32 v214, v214, v120
	v_add_f32_e32 v216, v216, v121
	v_mov_b32_e32 v167, v163
	v_add_f32_e32 v129, v129, v105
	v_add_f32_e32 v213, v213, v106
	v_add_f32_e32 v214, v214, v107
	v_add_f32_e32 v216, v216, v108
	v_lshl_add_u64 v[168:169], v[168:169], 0, v[162:163]
	v_add_f32_e32 v129, v129, v122
	v_add_f32_e32 v213, v213, v123
	v_add_f32_e32 v214, v214, v124
	v_add_f32_e32 v216, v216, v125
	v_lshl_add_u64 v[170:171], v[170:171], 0, v[164:165]
	v_add_f32_e32 v129, v129, v109
	v_add_f32_e32 v213, v213, v110
	v_add_f32_e32 v214, v214, v111
	v_add_f32_e32 v216, v216, v112
	v_lshl_add_u64 v[172:173], v[172:173], 0, v[166:167]
	v_add_f32_e32 v129, v129, v126
	v_add_f32_e32 v213, v213, v127
	v_add_f32_e32 v214, v214, v128
	v_add_f32_e32 v216, v216, v113
	v_lshl_add_u64 v[180:181], v[174:175], 0, s[76:77]
	v_add_f32_e32 v129, v129, v213
	v_add_f32_e32 v213, v214, v216
	v_lshl_add_u64 v[178:179], v[176:177], 0, s[76:77]
	v_add_f32_e32 v213, v129, v213
	v_cvt_pk_bf16_f32 v98, v114, v98
	v_cvt_pk_bf16_f32 v99, v99, v100
	v_cvt_pk_bf16_f32 v100, v101, v102
	v_cvt_pk_bf16_f32 v101, v103, v104
	v_cvt_pk_bf16_f32 v102, v105, v106
	s_nop 0
	v_mov_b32_e32 v214, v213
	s_nop 1
	v_permlane32_swap_b32_e32 v213, v214
	v_cvt_pk_bf16_f32 v103, v107, v108
	v_cvt_pk_bf16_f32 v104, v109, v110
	v_cvt_pk_bf16_f32 v105, v111, v112
	v_cvt_pk_bf16_f32 v106, v215, v115
	v_cvt_pk_bf16_f32 v107, v116, v117
	v_cvt_pk_bf16_f32 v108, v118, v119
	v_cvt_pk_bf16_f32 v109, v120, v121
	v_cvt_pk_bf16_f32 v110, v122, v123
	v_cvt_pk_bf16_f32 v111, v124, v125
	v_cvt_pk_bf16_f32 v112, v126, v127
	v_cvt_pk_bf16_f32 v113, v128, v113
	v_permlane32_swap_b32_e32 v98, v100
	v_permlane32_swap_b32_e32 v99, v101
	v_permlane32_swap_b32_e32 v102, v104
	v_permlane32_swap_b32_e32 v103, v105
	v_permlane32_swap_b32_e32 v106, v108
	v_permlane32_swap_b32_e32 v107, v109
	v_permlane32_swap_b32_e32 v110, v112
	v_permlane32_swap_b32_e32 v111, v113
	ds_read_b64_tr_b16 v[114:115], v190 offset:0x4000
	ds_read_b64_tr_b16 v[116:117], v190 offset:0x4800
	ds_read_b64_tr_b16 v[118:119], v190 offset:0x5000
	ds_read_b64_tr_b16 v[120:121], v190 offset:0x5800
	ds_read_b64_tr_b16 v[122:123], v190 offset:0x6000
	ds_read_b64_tr_b16 v[124:125], v190 offset:0x6800
	ds_read_b64_tr_b16 v[126:127], v190 offset:0x7000
	ds_read_b64_tr_b16 v[128:129], v190 offset:0x7800
	ds_read_b64_tr_b16 v[216:217], v190 offset:0x4200
	ds_read_b64_tr_b16 v[218:219], v190 offset:0x4a00
	ds_read_b64_tr_b16 v[220:221], v190 offset:0x5200
	ds_read_b64_tr_b16 v[222:223], v190 offset:0x5a00
	ds_read_b64_tr_b16 v[224:225], v190 offset:0x6200
	ds_read_b64_tr_b16 v[226:227], v190 offset:0x6a00
	ds_read_b64_tr_b16 v[228:229], v190 offset:0x7200
	ds_read_b64_tr_b16 v[230:231], v190 offset:0x7a00
	s_waitcnt lgkmcnt(8)
	s_nop 0
	v_mfma_f32_32x32x16_bf16 v[18:33], v[98:101], v[114:117], v[18:33]
	v_mfma_f32_32x32x16_bf16 v[18:33], v[102:105], v[118:121], v[18:33]
	v_mfma_f32_32x32x16_bf16 v[18:33], v[106:109], v[122:125], v[18:33]
	v_mfma_f32_32x32x16_bf16 v[18:33], v[110:113], v[126:129], v[18:33]
	ds_read_b64_tr_b16 v[114:115], v190 offset:0x4400
	ds_read_b64_tr_b16 v[116:117], v190 offset:0x4c00
	ds_read_b64_tr_b16 v[118:119], v190 offset:0x5400
	ds_read_b64_tr_b16 v[120:121], v190 offset:0x5c00
	ds_read_b64_tr_b16 v[122:123], v190 offset:0x6400
	ds_read_b64_tr_b16 v[124:125], v190 offset:0x6c00
	ds_read_b64_tr_b16 v[126:127], v190 offset:0x7400
	ds_read_b64_tr_b16 v[128:129], v190 offset:0x7c00
	s_waitcnt lgkmcnt(8)
	v_mfma_f32_32x32x16_bf16 v[34:49], v[98:101], v[216:219], v[34:49]
	v_mfma_f32_32x32x16_bf16 v[34:49], v[102:105], v[220:223], v[34:49]
	v_mfma_f32_32x32x16_bf16 v[34:49], v[106:109], v[224:227], v[34:49]
	v_mfma_f32_32x32x16_bf16 v[34:49], v[110:113], v[228:231], v[34:49]
	ds_read_b64_tr_b16 v[216:217], v190 offset:0x4600
	ds_read_b64_tr_b16 v[218:219], v190 offset:0x4e00
	ds_read_b64_tr_b16 v[220:221], v190 offset:0x5600
	ds_read_b64_tr_b16 v[222:223], v190 offset:0x5e00
	ds_read_b64_tr_b16 v[224:225], v190 offset:0x6600
	ds_read_b64_tr_b16 v[226:227], v190 offset:0x6e00
	ds_read_b64_tr_b16 v[228:229], v190 offset:0x7600
	ds_read_b64_tr_b16 v[230:231], v190 offset:0x7e00
	s_waitcnt lgkmcnt(8)
	v_mfma_f32_32x32x16_bf16 v[50:65], v[98:101], v[114:117], v[50:65]
	v_mfma_f32_32x32x16_bf16 v[50:65], v[102:105], v[118:121], v[50:65]
	v_mfma_f32_32x32x16_bf16 v[50:65], v[106:109], v[122:125], v[50:65]
	v_mfma_f32_32x32x16_bf16 v[50:65], v[110:113], v[126:129], v[50:65]
	s_waitcnt lgkmcnt(0)
	v_mfma_f32_32x32x16_bf16 v[66:81], v[98:101], v[216:219], v[66:81]
	s_waitcnt vmcnt(0)
	s_cmp_lt_u32 s11, s10
	s_cselect_b64 s[0:1], -1, 0
	s_cmp_ge_u32 s11, s10
	s_barrier
	v_mfma_f32_32x32x16_bf16 v[66:81], v[102:105], v[220:223], v[66:81]
	v_mfma_f32_32x32x16_bf16 v[66:81], v[106:109], v[224:227], v[66:81]
	v_mfma_f32_32x32x16_bf16 v[66:81], v[110:113], v[228:231], v[66:81]
	s_cbranch_scc1 .LBB0_1433
	s_add_i32 s13, s86, 0x4000
	s_mov_b32 s14, m0
	s_mov_b32 m0, s13
	s_nop 0
	global_load_lds_dwordx4 v[180:181], off
	s_mov_b32 m0, s14
	s_add_i32 s13, s3, 0x4000
	s_mov_b32 s14, m0
	s_mov_b32 m0, s13
	s_nop 0
	global_load_lds_dwordx4 v[178:179], off
	s_mov_b32 m0, s14
	v_lshl_add_u64 v[174:175], v[174:175], 0, s[30:31]
	v_lshl_add_u64 v[176:177], v[176:177], 0, s[30:31]
	s_branch .LBB0_1434

.LBB0_1434:
	ds_read_b128 v[178:181], v194 offset:32768
	ds_read_b128 v[216:219], v194 offset:45056
	ds_read_b128 v[238:241], v195 offset:32768
	ds_read_b128 v[242:245], v195 offset:45056
	ds_read_b128 v[246:249], v196 offset:32768
	ds_read_b128 v[250:253], v196 offset:45056
	ds_read_b128 v[220:223], v193
	ds_read_b128 v[224:227], v193 offset:1024
	ds_read_b128 v[228:231], v193 offset:2048
	ds_read_b128 v[232:235], v193 offset:3072
	s_waitcnt lgkmcnt(9)
	v_mfma_f32_32x32x16_bf16 v[114:129], v[178:181], v[158:161], v[82:97]
	s_waitcnt lgkmcnt(8)
	v_mfma_f32_32x32x16_bf16 v[98:113], v[216:219], v[158:161], v[82:97]
	ds_read_b128 v[178:181], v197 offset:32768
	ds_read_b128 v[216:219], v197 offset:45056
	s_waitcnt lgkmcnt(9)
	v_mfma_f32_32x32x16_bf16 v[114:129], v[238:241], v[154:157], v[114:129]
	s_waitcnt lgkmcnt(8)
	v_mfma_f32_32x32x16_bf16 v[98:113], v[242:245], v[154:157], v[98:113]
	ds_read_b128 v[238:241], v194 offset:32896
	ds_read_b128 v[242:245], v194 offset:45184
	s_waitcnt lgkmcnt(9)
	v_mfma_f32_32x32x16_bf16 v[114:129], v[246:249], v[150:153], v[114:129]
	s_waitcnt lgkmcnt(8)
	v_mfma_f32_32x32x16_bf16 v[98:113], v[250:253], v[150:153], v[98:113]
	ds_read_b128 v[246:249], v195 offset:32896
	ds_read_b128 v[250:253], v195 offset:45184
	s_waitcnt lgkmcnt(5)
	v_mfma_f32_32x32x16_bf16 v[114:129], v[178:181], v[146:149], v[114:129]
	s_waitcnt lgkmcnt(4)
	v_mfma_f32_32x32x16_bf16 v[98:113], v[216:219], v[146:149], v[98:113]
	ds_read_b128 v[178:181], v196 offset:32896
	ds_read_b128 v[216:219], v196 offset:45184
	s_cmp_ge_u32 s11, s10
	s_cbranch_scc1 .Lspr_k1
	s_add_i32 s13, s74, 0xe000
	s_mov_b32 s14, m0
	s_mov_b32 m0, s13
	s_nop 0
	global_load_lds_dwordx4 v[168:169], off
	s_mov_b32 m0, s14
.Lspr_k1:
	s_waitcnt lgkmcnt(5)
	v_mfma_f32_32x32x16_bf16 v[114:129], v[238:241], v[142:145], v[114:129]
	s_waitcnt lgkmcnt(4)
	v_mfma_f32_32x32x16_bf16 v[98:113], v[242:245], v[142:145], v[98:113]
	ds_read_b128 v[238:241], v197 offset:32896
	ds_read_b128 v[242:245], v197 offset:45184
	s_waitcnt lgkmcnt(5)
	v_mfma_f32_32x32x16_bf16 v[114:129], v[246:249], v[138:141], v[114:129]
	s_waitcnt lgkmcnt(4)
	v_mfma_f32_32x32x16_bf16 v[98:113], v[250:253], v[138:141], v[98:113]
	ds_read_b128 v[246:249], v194 offset:33024
	ds_read_b128 v[250:253], v194 offset:45312
	s_waitcnt lgkmcnt(5)
	v_mfma_f32_32x32x16_bf16 v[114:129], v[178:181], v[134:137], v[114:129]
	s_waitcnt lgkmcnt(4)
	v_mfma_f32_32x32x16_bf16 v[98:113], v[216:219], v[134:137], v[98:113]
	ds_read_b128 v[178:181], v195 offset:33024
	ds_read_b128 v[216:219], v195 offset:45312
	s_waitcnt lgkmcnt(5)
	v_mfma_f32_32x32x16_bf16 v[114:129], v[238:241], v[130:133], v[114:129]
	s_waitcnt lgkmcnt(4)
	v_mfma_f32_32x32x16_bf16 v[98:113], v[242:245], v[130:133], v[98:113]
	ds_read_b128 v[238:241], v196 offset:33024
	ds_read_b128 v[242:245], v196 offset:45312
	s_cmp_ge_u32 s11, s10
	s_cbranch_scc1 .Lspr_k2
	s_add_i32 s13, s75, 0xe000
	s_mov_b32 s14, m0
	s_mov_b32 m0, s13
	s_nop 0
	global_load_lds_dwordx4 v[170:171], off
	s_mov_b32 m0, s14
.Lspr_k2:
	s_waitcnt lgkmcnt(5)
	v_mfma_f32_32x32x16_bf16 v[114:129], v[246:249], v[220:223], v[114:129]
	s_waitcnt lgkmcnt(4)
	v_mfma_f32_32x32x16_bf16 v[98:113], v[250:253], v[220:223], v[98:113]
	ds_read_b128 v[246:249], v197 offset:33024
	ds_read_b128 v[250:253], v197 offset:45312
	s_waitcnt lgkmcnt(5)
	v_mfma_f32_32x32x16_bf16 v[114:129], v[178:181], v[224:227], v[114:129]
	s_waitcnt lgkmcnt(4)
	v_mfma_f32_32x32x16_bf16 v[98:113], v[216:219], v[224:227], v[98:113]
	s_waitcnt lgkmcnt(3)
	v_mfma_f32_32x32x16_bf16 v[114:129], v[238:241], v[228:231], v[114:129]
	s_waitcnt lgkmcnt(2)
	v_mfma_f32_32x32x16_bf16 v[98:113], v[242:245], v[228:231], v[98:113]
	s_waitcnt lgkmcnt(1)
	v_mfma_f32_32x32x16_bf16 v[114:129], v[246:249], v[232:235], v[114:129]
	s_waitcnt lgkmcnt(0)
	v_mfma_f32_32x32x16_bf16 v[98:113], v[250:253], v[232:235], v[98:113]
	s_cmp_ge_u32 s11, s10
	s_cbranch_scc1 .Lspr_k3
	s_add_i32 s13, s5, 0xe000
	s_mov_b32 s14, m0
	s_mov_b32 m0, s13
	s_nop 0
	global_load_lds_dwordx4 v[172:173], off
	s_mov_b32 m0, s14
	v_mov_b32_e32 v165, v163
	v_mov_b32_e32 v167, v163
	v_lshl_add_u64 v[168:169], v[168:169], 0, v[162:163]
	v_lshl_add_u64 v[170:171], v[170:171], 0, v[164:165]
	v_lshl_add_u64 v[172:173], v[172:173], 0, v[166:167]
